# v46 + O3 kv-up epilogue: all rope-gain loads issued with the k_nope gains (3 dependent round trips removed); prologue vmcnt(0) before the 6th DMA removed
# speedup vs baseline: 1.0043x; 1.0043x over previous
.LBB0_494:
	s_mul_hi_i32 s0, s8, 0x92492493
	s_add_i32 s0, s0, s8
	s_lshr_b32 s1, s0, 31
	s_ashr_i32 s0, s0, 6
	s_add_i32 s16, s0, s1
	s_mul_i32 s0, s16, 0x70
	s_sub_i32 s9, s8, s0
	s_cmpk_lt_i32 s9, 0x60
	s_cselect_b64 s[2:3], -1, 0
	s_cmpk_gt_i32 s9, 0x5f
	s_cselect_b64 s[0:1], -1, 0
	s_and_b64 s[10:11], s[2:3], exec
	s_cselect_b32 s13, s7, s5
	s_cselect_b32 s12, s6, s4
	s_lshl_b32 s9, s9, 7
	v_mov_b32_e32 v6, v155
	s_add_i32 s10, s9, 0xffffd000
	s_and_b64 s[2:3], s[2:3], exec
	v_ashrrev_i32_e32 v0, 6, v6
	v_lshrrev_b32_e32 v1, 31, v6
	v_add_u32_e32 v7, v0, v1
	s_cselect_b32 s9, s9, s10
	v_and_b32_e32 v1, 0x1fffffe, v7
	v_ashrrev_i32_e32 v2, 3, v6
	v_sub_u32_e32 v8, v0, v1
	v_lshrrev_b32_e32 v9, 4, v6
	v_add_u32_e32 v0, s9, v2
	v_xor_b32_e32 v3, v9, v6
	v_ashrrev_i32_e32 v1, 31, v0
	v_lshlrev_b64 v[0:1], 9, v[0:1]
	v_lshlrev_b32_e32 v3, 4, v3
	v_lshlrev_b32_e32 v72, 4, v6
	s_lshl_b32 s10, s16, 8
	v_lshl_add_u64 v[0:1], s[12:13], 0, v[0:1]
	v_and_b32_e32 v128, 0x70, v3
	v_readfirstlane_b32 s2, v72
	v_add_u32_e32 v10, 0x2000, v72
	v_lshl_add_u64 v[64:65], v[0:1], 0, v[128:129]
	v_add_u32_e32 v0, s10, v2
	s_mov_b32 m0, s2
	s_mov_b64 s[12:13], 0x8000
	v_readfirstlane_b32 s2, v10
	v_ashrrev_i32_e32 v1, 31, v0
	s_barrier
	global_load_lds_dwordx4 v[64:65], off
	v_lshl_add_u64 v[4:5], v[64:65], 0, s[12:13]
	s_mov_b32 m0, s2
	v_lshlrev_b64 v[0:1], 9, v[0:1]
	global_load_lds_dwordx4 v[4:5], off
	v_add_u32_e32 v4, 0x4000, v72
	v_lshl_add_u64 v[2:3], s[68:69], 0, v[0:1]
	v_readfirstlane_b32 s2, v4
	v_add_u32_e32 v10, 0x6000, v72
	v_lshl_add_u64 v[2:3], v[2:3], 0, v[128:129]
	s_mov_b32 m0, s2
	v_readfirstlane_b32 s2, v10
	global_load_lds_dwordx4 v[2:3], off
	v_lshl_add_u64 v[4:5], v[2:3], 0, s[12:13]
	s_mov_b32 m0, s2
	s_mov_b64 s[2:3], 0x10000
	v_add_u32_e32 v10, 0x8000, v72
	global_load_lds_dwordx4 v[4:5], off
	v_lshl_add_u64 v[4:5], v[2:3], 0, s[2:3]
	v_readfirstlane_b32 s2, v10
	s_mov_b32 m0, s2
	s_mov_b64 s[2:3], 0x18000
	global_load_lds_dwordx4 v[4:5], off
	v_add_u32_e32 v4, 0xa000, v72
	v_lshl_add_u64 v[2:3], v[2:3], 0, s[2:3]
	v_readfirstlane_b32 s2, v4
	s_mov_b32 m0, s2
	v_bfe_u32 v87, v6, 5, 1
	global_load_lds_dwordx4 v[2:3], off
	v_lshrrev_b32_e32 v2, 1, v6
	v_bfe_u32 v3, v6, 1, 3
	v_bitop3_b32 v2, v87, v2, 7 bitop3:0x78
	v_lshlrev_b32_e32 v75, 4, v2
	v_bitop3_b32 v2, v87, v3, 2 bitop3:0x36
	v_and_b32_e32 v68, 31, v6
	v_lshlrev_b32_e32 v69, 7, v8
	v_lshlrev_b32_e32 v74, 4, v2
	v_bitop3_b32 v2, v87, v3, 4 bitop3:0x36
	v_or_b32_e32 v4, v69, v68
	v_lshlrev_b32_e32 v73, 4, v2
	v_bitop3_b32 v2, v87, v3, 6 bitop3:0x36
	v_lshlrev_b32_e32 v76, 7, v4
	v_lshlrev_b32_e32 v4, 4, v7
	s_movk_i32 s2, 0xffe0
	v_lshlrev_b32_e32 v71, 4, v2
	v_bitop3_b32 v2, v9, 7, v6 bitop3:0x48
	v_and_b32_e32 v70, 0xffffffe0, v4
	v_bfi_b32 v4, s2, v4, v6
	v_lshl_or_b32 v0, v2, 4, v0
	v_mov_b32_e32 v48, 0
	v_and_b32_e32 v94, 63, v6
	v_lshlrev_b32_e32 v77, 7, v4
	v_add_u32_e32 v78, 0x4000, v76
	v_lshl_add_u64 v[66:67], s[14:15], 0, v[0:1]
	s_mov_b32 s11, 0
	s_mov_b64 s[2:3], 0
	v_mov_b32_e32 v49, v48
	v_mov_b32_e32 v50, v48
	v_mov_b32_e32 v51, v48
	v_mov_b32_e32 v52, v48
	v_mov_b32_e32 v53, v48
	v_mov_b32_e32 v54, v48
	v_mov_b32_e32 v55, v48
	v_mov_b32_e32 v56, v48
	v_mov_b32_e32 v57, v48
	v_mov_b32_e32 v58, v48
	v_mov_b32_e32 v59, v48
	v_mov_b32_e32 v60, v48
	v_mov_b32_e32 v61, v48
	v_mov_b32_e32 v62, v48
	v_mov_b32_e32 v63, v48
	v_mov_b32_e32 v32, v48
	v_mov_b32_e32 v33, v48
	v_mov_b32_e32 v34, v48
	v_mov_b32_e32 v35, v48
	v_mov_b32_e32 v36, v48
	v_mov_b32_e32 v37, v48
	v_mov_b32_e32 v38, v48
	v_mov_b32_e32 v39, v48
	v_mov_b32_e32 v40, v48
	v_mov_b32_e32 v41, v48
	v_mov_b32_e32 v42, v48
	v_mov_b32_e32 v43, v48
	v_mov_b32_e32 v44, v48
	v_mov_b32_e32 v45, v48
	v_mov_b32_e32 v46, v48
	v_mov_b32_e32 v47, v48
	v_mov_b32_e32 v0, v48
	v_mov_b32_e32 v1, v48
	v_mov_b32_e32 v2, v48
	v_mov_b32_e32 v3, v48
	v_mov_b32_e32 v4, v48
	v_mov_b32_e32 v5, v48
	v_mov_b32_e32 v6, v48
	v_mov_b32_e32 v7, v48
	v_mov_b32_e32 v8, v48
	v_mov_b32_e32 v9, v48
	v_mov_b32_e32 v10, v48
	v_mov_b32_e32 v11, v48
	v_mov_b32_e32 v12, v48
	v_mov_b32_e32 v13, v48
	v_mov_b32_e32 v14, v48
	v_mov_b32_e32 v15, v48
	v_mov_b32_e32 v16, v48
	v_mov_b32_e32 v17, v48
	v_mov_b32_e32 v18, v48
	v_mov_b32_e32 v19, v48
	v_mov_b32_e32 v20, v48
	v_mov_b32_e32 v21, v48
	v_mov_b32_e32 v22, v48
	v_mov_b32_e32 v23, v48
	v_mov_b32_e32 v24, v48
	v_mov_b32_e32 v25, v48
	v_mov_b32_e32 v26, v48
	v_mov_b32_e32 v27, v48
	v_mov_b32_e32 v28, v48
	v_mov_b32_e32 v29, v48
	v_mov_b32_e32 v30, v48
	v_mov_b32_e32 v31, v48
	s_mov_b64 s[16:17], 0x80
	v_add_u32_e32 v246, 0xc000, v72
	v_lshl_add_u64 v[244:245], v[64:65], 0, s[2:3]
	v_lshl_add_u64 v[244:245], v[244:245], 0, s[16:17]
	v_readfirstlane_b32 s12, v246
	s_mov_b32 m0, s12
	s_nop 0
	global_load_lds_dwordx4 v[244:245], off
	v_add_u32_e32 v243, 0x2000, v246
	s_mov_b64 s[12:13], 0x8080
	v_lshl_add_u64 v[244:245], v[64:65], 0, s[2:3]
	v_lshl_add_u64 v[244:245], v[244:245], 0, s[12:13]
	v_readfirstlane_b32 s12, v243
	s_mov_b32 m0, s12
	s_nop 0
	global_load_lds_dwordx4 v[244:245], off
	v_add_u32_e32 v243, 0x4000, v246
	s_mov_b64 s[12:13], 0x6994080
	v_lshl_add_u64 v[244:245], v[66:67], 0, s[2:3]
	v_lshl_add_u64 v[244:245], v[244:245], 0, s[12:13]
	v_readfirstlane_b32 s12, v243
	s_mov_b32 m0, s12
	s_nop 0
	global_load_lds_dwordx4 v[244:245], off
	v_add_u32_e32 v243, 0x6000, v246
	s_mov_b64 s[12:13], 0x699c080
	v_lshl_add_u64 v[244:245], v[66:67], 0, s[2:3]
	v_lshl_add_u64 v[244:245], v[244:245], 0, s[12:13]
	v_readfirstlane_b32 s12, v243
	s_mov_b32 m0, s12
	s_nop 0
	global_load_lds_dwordx4 v[244:245], off
	v_add_u32_e32 v243, 0x8000, v246
	s_mov_b64 s[12:13], 0x69a4080
	v_lshl_add_u64 v[244:245], v[66:67], 0, s[2:3]
	v_lshl_add_u64 v[244:245], v[244:245], 0, s[12:13]
	v_readfirstlane_b32 s12, v243
	s_mov_b32 m0, s12
	s_nop 0
	global_load_lds_dwordx4 v[244:245], off
	v_add_u32_e32 v243, 0xa000, v246
	s_mov_b64 s[12:13], 0x69ac080
	v_lshl_add_u64 v[244:245], v[66:67], 0, s[2:3]
	v_lshl_add_u64 v[244:245], v[244:245], 0, s[12:13]
	v_readfirstlane_b32 s12, v243
	s_mov_b32 m0, s12
	s_nop 0
	global_load_lds_dwordx4 v[244:245], off
	s_add_u32 s2, s2, 0x80
	s_addc_u32 s3, s3, 0
	s_waitcnt vmcnt(6) lgkmcnt(0)
	s_barrier
	v_mov_b32_e32 v184, v78
	v_mov_b32_e32 v154, v77
	v_add_u32_e32 v246, 0x18000, v72
	v_add_u32_e32 v181, v184, v75
	ds_read_b128 v[80:83], v181 offset:0x0
	ds_read_b128 v[88:91], v181 offset:0x1000
	ds_read_b128 v[96:99], v181 offset:0x2000
	ds_read_b128 v[100:103], v181 offset:0x3000
	v_add_u32_e32 v181, v154, v75
	ds_read_b128 v[104:107], v181 offset:0
	v_add_u32_e32 v181, v184, v74
	ds_read_b128 v[108:111], v181 offset:0x0
	ds_read_b128 v[112:115], v181 offset:0x1000
	ds_read_b128 v[116:119], v181 offset:0x2000
	ds_read_b128 v[120:123], v181 offset:0x3000
	v_add_u32_e32 v181, v154, v74
	ds_read_b128 v[124:127], v181 offset:0
	s_waitcnt lgkmcnt(5)
	v_mfma_f32_32x32x16_bf16 v[48:63], v[80:83], v[104:107], v[48:63]
	v_lshl_add_u64 v[244:245], v[64:65], 0, s[2:3]
	v_lshl_add_u64 v[244:245], v[244:245], 0, s[16:17]
	v_readfirstlane_b32 s12, v246
	s_mov_b32 m0, s12
	s_nop 0
	global_load_lds_dwordx4 v[244:245], off
	v_mfma_f32_32x32x16_bf16 v[32:47], v[88:91], v[104:107], v[32:47]
	v_mfma_f32_32x32x16_bf16 v[0:15], v[96:99], v[104:107], v[0:15]
	v_add_u32_e32 v243, 0x2000, v246
	s_mov_b64 s[12:13], 0x8080
	v_lshl_add_u64 v[244:245], v[64:65], 0, s[2:3]
	v_lshl_add_u64 v[244:245], v[244:245], 0, s[12:13]
	v_readfirstlane_b32 s12, v243
	s_mov_b32 m0, s12
	s_nop 0
	global_load_lds_dwordx4 v[244:245], off
	v_mfma_f32_32x32x16_bf16 v[16:31], v[100:103], v[104:107], v[16:31]
	v_add_u32_e32 v181, v184, v73
	ds_read_b128 v[80:83], v181 offset:0x0
	ds_read_b128 v[88:91], v181 offset:0x1000
	ds_read_b128 v[96:99], v181 offset:0x2000
	ds_read_b128 v[100:103], v181 offset:0x3000
	v_add_u32_e32 v181, v154, v73
	ds_read_b128 v[104:107], v181 offset:0
	s_waitcnt lgkmcnt(5)
	v_mfma_f32_32x32x16_bf16 v[48:63], v[108:111], v[124:127], v[48:63]
	v_add_u32_e32 v243, 0x4000, v246
	s_mov_b64 s[12:13], 0x6994080
	v_lshl_add_u64 v[244:245], v[66:67], 0, s[2:3]
	v_lshl_add_u64 v[244:245], v[244:245], 0, s[12:13]
	v_readfirstlane_b32 s12, v243
	s_mov_b32 m0, s12
	s_nop 0
	global_load_lds_dwordx4 v[244:245], off
	v_mfma_f32_32x32x16_bf16 v[32:47], v[112:115], v[124:127], v[32:47]
	v_mfma_f32_32x32x16_bf16 v[0:15], v[116:119], v[124:127], v[0:15]
	v_add_u32_e32 v243, 0x6000, v246
	s_mov_b64 s[12:13], 0x699c080
	v_lshl_add_u64 v[244:245], v[66:67], 0, s[2:3]
	v_lshl_add_u64 v[244:245], v[244:245], 0, s[12:13]
	v_readfirstlane_b32 s12, v243
	s_mov_b32 m0, s12
	s_nop 0
	global_load_lds_dwordx4 v[244:245], off
	v_mfma_f32_32x32x16_bf16 v[16:31], v[120:123], v[124:127], v[16:31]
	v_add_u32_e32 v181, v184, v71
	ds_read_b128 v[108:111], v181 offset:0x0
	ds_read_b128 v[112:115], v181 offset:0x1000
	ds_read_b128 v[116:119], v181 offset:0x2000
	ds_read_b128 v[120:123], v181 offset:0x3000
	v_add_u32_e32 v181, v154, v71
	ds_read_b128 v[124:127], v181 offset:0
	s_waitcnt lgkmcnt(5)
	v_mfma_f32_32x32x16_bf16 v[48:63], v[80:83], v[104:107], v[48:63]
	v_add_u32_e32 v243, 0x8000, v246
	s_mov_b64 s[12:13], 0x69a4080
	v_lshl_add_u64 v[244:245], v[66:67], 0, s[2:3]
	v_lshl_add_u64 v[244:245], v[244:245], 0, s[12:13]
	v_readfirstlane_b32 s12, v243
	s_mov_b32 m0, s12
	s_nop 0
	global_load_lds_dwordx4 v[244:245], off
	v_mfma_f32_32x32x16_bf16 v[32:47], v[88:91], v[104:107], v[32:47]
	v_mfma_f32_32x32x16_bf16 v[0:15], v[96:99], v[104:107], v[0:15]
	v_add_u32_e32 v243, 0xa000, v246
	s_mov_b64 s[12:13], 0x69ac080
	v_lshl_add_u64 v[244:245], v[66:67], 0, s[2:3]
	v_lshl_add_u64 v[244:245], v[244:245], 0, s[12:13]
	v_readfirstlane_b32 s12, v243
	s_mov_b32 m0, s12
	s_nop 0
	global_load_lds_dwordx4 v[244:245], off
	v_mfma_f32_32x32x16_bf16 v[16:31], v[100:103], v[104:107], v[16:31]
	s_waitcnt lgkmcnt(0)
	v_mfma_f32_32x32x16_bf16 v[48:63], v[108:111], v[124:127], v[48:63]
	v_mfma_f32_32x32x16_bf16 v[32:47], v[112:115], v[124:127], v[32:47]
	v_mfma_f32_32x32x16_bf16 v[0:15], v[116:119], v[124:127], v[0:15]
	v_mfma_f32_32x32x16_bf16 v[16:31], v[120:123], v[124:127], v[16:31]
	s_add_u32 s2, s2, 0x80
	s_addc_u32 s3, s3, 0
	s_waitcnt vmcnt(6) lgkmcnt(0)
	s_barrier
	v_add_u32_e32 v184, 0xc000, v78
	v_add_u32_e32 v154, 0xc000, v77
	v_mov_b32_e32 v246, v72
	v_add_u32_e32 v181, v184, v75
	ds_read_b128 v[80:83], v181 offset:0x0
	ds_read_b128 v[88:91], v181 offset:0x1000
	ds_read_b128 v[96:99], v181 offset:0x2000
	ds_read_b128 v[100:103], v181 offset:0x3000
	v_add_u32_e32 v181, v154, v75
	ds_read_b128 v[104:107], v181 offset:0
	v_add_u32_e32 v181, v184, v74
	ds_read_b128 v[108:111], v181 offset:0x0
	ds_read_b128 v[112:115], v181 offset:0x1000
	ds_read_b128 v[116:119], v181 offset:0x2000
	ds_read_b128 v[120:123], v181 offset:0x3000
	v_add_u32_e32 v181, v154, v74
	ds_read_b128 v[124:127], v181 offset:0
	s_waitcnt lgkmcnt(5)
	v_mfma_f32_32x32x16_bf16 v[48:63], v[80:83], v[104:107], v[48:63]
	v_lshl_add_u64 v[244:245], v[64:65], 0, s[2:3]
	v_lshl_add_u64 v[244:245], v[244:245], 0, s[16:17]
	v_readfirstlane_b32 s12, v246
	s_mov_b32 m0, s12
	s_nop 0
	global_load_lds_dwordx4 v[244:245], off
	v_mfma_f32_32x32x16_bf16 v[32:47], v[88:91], v[104:107], v[32:47]
	v_mfma_f32_32x32x16_bf16 v[0:15], v[96:99], v[104:107], v[0:15]
	v_add_u32_e32 v243, 0x2000, v246
	s_mov_b64 s[12:13], 0x8080
	v_lshl_add_u64 v[244:245], v[64:65], 0, s[2:3]
	v_lshl_add_u64 v[244:245], v[244:245], 0, s[12:13]
	v_readfirstlane_b32 s12, v243
	s_mov_b32 m0, s12
	s_nop 0
	global_load_lds_dwordx4 v[244:245], off
	v_mfma_f32_32x32x16_bf16 v[16:31], v[100:103], v[104:107], v[16:31]
	v_add_u32_e32 v181, v184, v73
	ds_read_b128 v[80:83], v181 offset:0x0
	ds_read_b128 v[88:91], v181 offset:0x1000
	ds_read_b128 v[96:99], v181 offset:0x2000
	ds_read_b128 v[100:103], v181 offset:0x3000
	v_add_u32_e32 v181, v154, v73
	ds_read_b128 v[104:107], v181 offset:0
	s_waitcnt lgkmcnt(5)
	v_mfma_f32_32x32x16_bf16 v[48:63], v[108:111], v[124:127], v[48:63]
	v_add_u32_e32 v243, 0x4000, v246
	s_mov_b64 s[12:13], 0x6994080
	v_lshl_add_u64 v[244:245], v[66:67], 0, s[2:3]
	v_lshl_add_u64 v[244:245], v[244:245], 0, s[12:13]
	v_readfirstlane_b32 s12, v243
	s_mov_b32 m0, s12
	s_nop 0
	global_load_lds_dwordx4 v[244:245], off
	v_mfma_f32_32x32x16_bf16 v[32:47], v[112:115], v[124:127], v[32:47]
	v_mfma_f32_32x32x16_bf16 v[0:15], v[116:119], v[124:127], v[0:15]
	v_add_u32_e32 v243, 0x6000, v246
	s_mov_b64 s[12:13], 0x699c080
	v_lshl_add_u64 v[244:245], v[66:67], 0, s[2:3]
	v_lshl_add_u64 v[244:245], v[244:245], 0, s[12:13]
	v_readfirstlane_b32 s12, v243
	s_mov_b32 m0, s12
	s_nop 0
	global_load_lds_dwordx4 v[244:245], off
	v_mfma_f32_32x32x16_bf16 v[16:31], v[120:123], v[124:127], v[16:31]
	v_add_u32_e32 v181, v184, v71
	ds_read_b128 v[108:111], v181 offset:0x0
	ds_read_b128 v[112:115], v181 offset:0x1000
	ds_read_b128 v[116:119], v181 offset:0x2000
	ds_read_b128 v[120:123], v181 offset:0x3000
	v_add_u32_e32 v181, v154, v71
	ds_read_b128 v[124:127], v181 offset:0
	s_waitcnt lgkmcnt(5)
	v_mfma_f32_32x32x16_bf16 v[48:63], v[80:83], v[104:107], v[48:63]
	v_add_u32_e32 v243, 0x8000, v246
	s_mov_b64 s[12:13], 0x69a4080
	v_lshl_add_u64 v[244:245], v[66:67], 0, s[2:3]
	v_lshl_add_u64 v[244:245], v[244:245], 0, s[12:13]
	v_readfirstlane_b32 s12, v243
	s_mov_b32 m0, s12
	s_nop 0
	global_load_lds_dwordx4 v[244:245], off
	v_mfma_f32_32x32x16_bf16 v[32:47], v[88:91], v[104:107], v[32:47]
	v_mfma_f32_32x32x16_bf16 v[0:15], v[96:99], v[104:107], v[0:15]
	v_add_u32_e32 v243, 0xa000, v246
	s_mov_b64 s[12:13], 0x69ac080
	v_lshl_add_u64 v[244:245], v[66:67], 0, s[2:3]
	v_lshl_add_u64 v[244:245], v[244:245], 0, s[12:13]
	v_readfirstlane_b32 s12, v243
	s_mov_b32 m0, s12
	s_nop 0
	global_load_lds_dwordx4 v[244:245], off
	v_mfma_f32_32x32x16_bf16 v[16:31], v[100:103], v[104:107], v[16:31]
	s_waitcnt lgkmcnt(0)
	v_mfma_f32_32x32x16_bf16 v[48:63], v[108:111], v[124:127], v[48:63]
	v_mfma_f32_32x32x16_bf16 v[32:47], v[112:115], v[124:127], v[32:47]
	v_mfma_f32_32x32x16_bf16 v[0:15], v[116:119], v[124:127], v[0:15]
	v_mfma_f32_32x32x16_bf16 v[16:31], v[120:123], v[124:127], v[16:31]
	s_add_u32 s2, s2, 0x80
	s_addc_u32 s3, s3, 0
	s_waitcnt vmcnt(6) lgkmcnt(0)
	s_barrier
	v_add_u32_e32 v184, 0x18000, v78
	v_add_u32_e32 v154, 0x18000, v77
	v_add_u32_e32 v181, v184, v75
	ds_read_b128 v[80:83], v181 offset:0x0
	ds_read_b128 v[88:91], v181 offset:0x1000
	ds_read_b128 v[96:99], v181 offset:0x2000
	ds_read_b128 v[100:103], v181 offset:0x3000
	v_add_u32_e32 v181, v154, v75
	ds_read_b128 v[104:107], v181 offset:0
	v_add_u32_e32 v181, v184, v74
	ds_read_b128 v[108:111], v181 offset:0x0
	ds_read_b128 v[112:115], v181 offset:0x1000
	ds_read_b128 v[116:119], v181 offset:0x2000
	ds_read_b128 v[120:123], v181 offset:0x3000
	v_add_u32_e32 v181, v154, v74
	ds_read_b128 v[124:127], v181 offset:0
	s_waitcnt lgkmcnt(5)
	v_mfma_f32_32x32x16_bf16 v[48:63], v[80:83], v[104:107], v[48:63]
	v_mfma_f32_32x32x16_bf16 v[32:47], v[88:91], v[104:107], v[32:47]
	v_mfma_f32_32x32x16_bf16 v[0:15], v[96:99], v[104:107], v[0:15]
	v_mfma_f32_32x32x16_bf16 v[16:31], v[100:103], v[104:107], v[16:31]
	v_add_u32_e32 v181, v184, v73
	ds_read_b128 v[80:83], v181 offset:0x0
	ds_read_b128 v[88:91], v181 offset:0x1000
	ds_read_b128 v[96:99], v181 offset:0x2000
	ds_read_b128 v[100:103], v181 offset:0x3000
	v_add_u32_e32 v181, v154, v73
	ds_read_b128 v[104:107], v181 offset:0
	s_waitcnt lgkmcnt(5)
	v_mfma_f32_32x32x16_bf16 v[48:63], v[108:111], v[124:127], v[48:63]
	v_mfma_f32_32x32x16_bf16 v[32:47], v[112:115], v[124:127], v[32:47]
	v_mfma_f32_32x32x16_bf16 v[0:15], v[116:119], v[124:127], v[0:15]
	v_mfma_f32_32x32x16_bf16 v[16:31], v[120:123], v[124:127], v[16:31]
	v_add_u32_e32 v181, v184, v71
	ds_read_b128 v[108:111], v181 offset:0x0
	ds_read_b128 v[112:115], v181 offset:0x1000
	ds_read_b128 v[116:119], v181 offset:0x2000
	ds_read_b128 v[120:123], v181 offset:0x3000
	v_add_u32_e32 v181, v154, v71
	ds_read_b128 v[124:127], v181 offset:0
	s_waitcnt lgkmcnt(5)
	v_mfma_f32_32x32x16_bf16 v[48:63], v[80:83], v[104:107], v[48:63]
	v_mfma_f32_32x32x16_bf16 v[32:47], v[88:91], v[104:107], v[32:47]
	v_mfma_f32_32x32x16_bf16 v[0:15], v[96:99], v[104:107], v[0:15]
	v_mfma_f32_32x32x16_bf16 v[16:31], v[100:103], v[104:107], v[16:31]
	s_waitcnt lgkmcnt(0)
	v_mfma_f32_32x32x16_bf16 v[48:63], v[108:111], v[124:127], v[48:63]
	v_mfma_f32_32x32x16_bf16 v[32:47], v[112:115], v[124:127], v[32:47]
	v_mfma_f32_32x32x16_bf16 v[0:15], v[116:119], v[124:127], v[0:15]
	v_mfma_f32_32x32x16_bf16 v[16:31], v[120:123], v[124:127], v[16:31]
	s_waitcnt vmcnt(0) lgkmcnt(0)
	s_barrier
	v_mov_b32_e32 v184, v78
	v_mov_b32_e32 v154, v77
	v_add_u32_e32 v181, v184, v75
	ds_read_b128 v[80:83], v181 offset:0x0
	ds_read_b128 v[88:91], v181 offset:0x1000
	ds_read_b128 v[96:99], v181 offset:0x2000
	ds_read_b128 v[100:103], v181 offset:0x3000
	v_add_u32_e32 v181, v154, v75
	ds_read_b128 v[104:107], v181 offset:0
	v_add_u32_e32 v181, v184, v74
	ds_read_b128 v[108:111], v181 offset:0x0
	ds_read_b128 v[112:115], v181 offset:0x1000
	ds_read_b128 v[116:119], v181 offset:0x2000
	ds_read_b128 v[120:123], v181 offset:0x3000
	v_add_u32_e32 v181, v154, v74
	ds_read_b128 v[124:127], v181 offset:0
	s_waitcnt lgkmcnt(5)
	v_mfma_f32_32x32x16_bf16 v[48:63], v[80:83], v[104:107], v[48:63]
	v_mfma_f32_32x32x16_bf16 v[32:47], v[88:91], v[104:107], v[32:47]
	v_mfma_f32_32x32x16_bf16 v[0:15], v[96:99], v[104:107], v[0:15]
	v_mfma_f32_32x32x16_bf16 v[16:31], v[100:103], v[104:107], v[16:31]
	v_add_u32_e32 v181, v184, v73
	ds_read_b128 v[80:83], v181 offset:0x0
	ds_read_b128 v[88:91], v181 offset:0x1000
	ds_read_b128 v[96:99], v181 offset:0x2000
	ds_read_b128 v[100:103], v181 offset:0x3000
	v_add_u32_e32 v181, v154, v73
	ds_read_b128 v[104:107], v181 offset:0
	s_waitcnt lgkmcnt(5)
	v_mfma_f32_32x32x16_bf16 v[48:63], v[108:111], v[124:127], v[48:63]
	v_mfma_f32_32x32x16_bf16 v[32:47], v[112:115], v[124:127], v[32:47]
	v_mfma_f32_32x32x16_bf16 v[0:15], v[116:119], v[124:127], v[0:15]
	v_mfma_f32_32x32x16_bf16 v[16:31], v[120:123], v[124:127], v[16:31]
	v_add_u32_e32 v181, v184, v71
	ds_read_b128 v[108:111], v181 offset:0x0
	ds_read_b128 v[112:115], v181 offset:0x1000
	ds_read_b128 v[116:119], v181 offset:0x2000
	ds_read_b128 v[120:123], v181 offset:0x3000
	v_add_u32_e32 v181, v154, v71
	ds_read_b128 v[124:127], v181 offset:0
	s_waitcnt lgkmcnt(5)
	v_mfma_f32_32x32x16_bf16 v[48:63], v[80:83], v[104:107], v[48:63]
	v_mfma_f32_32x32x16_bf16 v[32:47], v[88:91], v[104:107], v[32:47]
	v_mfma_f32_32x32x16_bf16 v[0:15], v[96:99], v[104:107], v[0:15]
	v_mfma_f32_32x32x16_bf16 v[16:31], v[100:103], v[104:107], v[16:31]
	s_waitcnt lgkmcnt(0)
	v_mfma_f32_32x32x16_bf16 v[48:63], v[108:111], v[124:127], v[48:63]
	v_mfma_f32_32x32x16_bf16 v[32:47], v[112:115], v[124:127], v[32:47]
	v_mfma_f32_32x32x16_bf16 v[0:15], v[116:119], v[124:127], v[0:15]
	v_mfma_f32_32x32x16_bf16 v[16:31], v[120:123], v[124:127], v[16:31]
	v_add_u32_e32 v64, s10, v69
	v_ashrrev_i32_e32 v69, 7, v64
	v_or_b32_e32 v64, s9, v68
	v_add_u32_e32 v64, v70, v64
	s_barrier
	s_andn2_b64 vcc, exec, s[0:1]
	s_mov_b64 s[0:1], -1
	s_cbranch_vccnz .LBB0_498
	v_ashrrev_i32_e32 v65, 8, v64
	v_lshl_add_u32 v68, v65, 3, v69
	s_movk_i32 s0, 0x500
	v_lshl_add_u32 v65, v65, 9, s72
	v_mad_i64_i32 v[70:71], s[0:1], v68, s0, 0
	v_or_b32_sdwa v66, v65, v64 dst_sel:DWORD dst_unused:UNUSED_PAD src0_sel:DWORD src1_sel:BYTE_0
	v_ashrrev_i32_e32 v67, 31, v66
	v_readlane_b32 s0, v242, 58
	v_or_b32_sdwa v70, v70, v64 dst_sel:DWORD dst_unused:UNUSED_PAD src0_sel:DWORD src1_sel:BYTE_0
	v_lshlrev_b64 v[66:67], 7, v[66:67]
	v_readlane_b32 s1, v242, 59
	v_mov_b64_e32 v[72:73], s[58:59]
	s_movk_i32 s2, 0xc0
	v_lshl_add_u64 v[66:67], s[0:1], 0, v[66:67]
	v_mad_u64_u32 v[84:85], s[0:1], v70, s2, v[72:73]
	v_mad_i32_i24 v85, v71, s2, v85
	v_mov_b64_e32 v[70:71], s[62:63]
	s_mov_b32 s0, 0x28000
	v_mad_i64_i32 v[70:71], s[0:1], v68, s0, v[70:71]
	v_lshlrev_b32_sdwa v128, v166, v64 dst_sel:DWORD dst_unused:UNUSED_PAD src0_sel:DWORD src1_sel:BYTE_0
	v_lshl_add_u64 v[80:81], v[70:71], 0, v[128:129]
	s_mov_b64 s[0:1], 0

.LBB0_505:
	v_lshlrev_b32_e32 v88, 5, v87
	v_mov_b32_e32 v89, v129
	v_lshl_add_u64 v[68:69], v[66:67], 0, v[88:89]
	global_load_dwordx4 v[72:75], v[68:69], off offset:64
	global_load_dwordx4 v[64:67], v[68:69], off offset:80
	global_load_dwordx4 v[76:79], v[68:69], off
	s_nop 0
	global_load_dwordx4 v[68:71], v[68:69], off offset:16
	v_lshlrev_b32_e32 v83, 4, v87
	v_pk_mul_f32 v[92:93], v[40:41], v[86:87] op_sel_hi:[1,0]
	v_pk_mul_f32 v[90:91], v[42:43], v[86:87] op_sel_hi:[1,0]
	v_pk_mul_f32 v[42:43], v[44:45], v[86:87] op_sel_hi:[1,0]
	v_pk_mul_f32 v[40:41], v[46:47], v[86:87] op_sel_hi:[1,0]
	v_pk_mul_f32 v[44:45], v[50:51], v[86:87] op_sel_hi:[1,0]
	v_pk_mul_f32 v[46:47], v[48:49], v[86:87] op_sel_hi:[1,0]
	v_pk_mul_f32 v[48:49], v[54:55], v[86:87] op_sel_hi:[1,0]
	v_pk_mul_f32 v[50:51], v[52:53], v[86:87] op_sel_hi:[1,0]
	v_pk_mul_f32 v[52:53], v[58:59], v[86:87] op_sel_hi:[1,0]
	v_pk_mul_f32 v[54:55], v[56:57], v[86:87] op_sel_hi:[1,0]
	v_pk_mul_f32 v[56:57], v[62:63], v[86:87] op_sel_hi:[1,0]
	v_pk_mul_f32 v[58:59], v[60:61], v[86:87] op_sel_hi:[1,0]
	v_pk_mul_f32 v[60:61], v[34:35], v[86:87] op_sel_hi:[1,0]
	v_pk_mul_f32 v[62:63], v[32:33], v[86:87] op_sel_hi:[1,0]
	global_load_dwordx4 v[198:201], v83, s[40:41]
	global_load_dwordx4 v[202:205], v83, s[40:41] offset:32
	global_load_dwordx4 v[206:209], v83, s[40:41] offset:64
	global_load_dwordx4 v[210:213], v83, s[40:41] offset:96
	global_load_dwordx4 v[214:217], v83, s[40:41] offset:128
	global_load_dwordx4 v[218:221], v83, s[40:41] offset:160
	global_load_dwordx4 v[222:225], v83, s[40:41] offset:192
	global_load_dwordx4 v[226:229], v83, s[40:41] offset:224
	global_load_dwordx2 v[230:231], v88, s[40:41] offset:320
	global_load_dwordx2 v[232:233], v88, s[40:41] offset:256
	global_load_dword v185, v88, s[40:41] offset:264
	global_load_dword v184, v88, s[40:41] offset:328
	global_load_dword v187, v88, s[40:41] offset:268
	global_load_dword v186, v88, s[40:41] offset:332
	global_load_dword v189, v88, s[40:41] offset:272
	global_load_dword v188, v88, s[40:41] offset:336
	global_load_dword v191, v88, s[40:41] offset:276
	global_load_dword v190, v88, s[40:41] offset:340
	global_load_dword v193, v88, s[40:41] offset:280
	global_load_dword v192, v88, s[40:41] offset:344
	global_load_dword v235, v88, s[40:41] offset:284
	global_load_dword v234, v88, s[40:41] offset:348
	v_pk_mul_f32 v[96:97], v[36:37], v[86:87] op_sel_hi:[1,0]
	v_mul_f32_e32 v36, v47, v47
	v_pk_fma_f32 v[36:37], v[46:47], v[46:47], v[36:37] op_sel_hi:[1,1,0]
	v_mul_f32_e32 v98, v45, v45
	v_pk_fma_f32 v[36:37], v[44:45], v[44:45], v[36:37]
	v_mul_f32_e32 v100, v51, v51
	v_pk_add_f32 v[36:37], v[98:99], v[36:37] op_sel_hi:[0,1]
	v_pk_fma_f32 v[36:37], v[50:51], v[50:51], v[36:37]
	v_mul_f32_e32 v102, v49, v49
	v_pk_add_f32 v[36:37], v[100:101], v[36:37] op_sel_hi:[0,1]
	v_pk_fma_f32 v[36:37], v[48:49], v[48:49], v[36:37]
	v_mul_f32_e32 v104, v55, v55
	v_pk_add_f32 v[36:37], v[102:103], v[36:37] op_sel_hi:[0,1]
	v_pk_fma_f32 v[36:37], v[54:55], v[54:55], v[36:37]
	v_mul_f32_e32 v106, v53, v53
	v_pk_add_f32 v[36:37], v[104:105], v[36:37] op_sel_hi:[0,1]
	v_pk_fma_f32 v[36:37], v[52:53], v[52:53], v[36:37]
	v_mul_f32_e32 v108, v59, v59
	v_pk_add_f32 v[36:37], v[106:107], v[36:37] op_sel_hi:[0,1]
	v_pk_fma_f32 v[36:37], v[58:59], v[58:59], v[36:37]
	v_mul_f32_e32 v110, v57, v57
	v_pk_add_f32 v[36:37], v[108:109], v[36:37] op_sel_hi:[0,1]
	v_pk_fma_f32 v[36:37], v[56:57], v[56:57], v[36:37]
	v_mul_f32_e32 v112, v63, v63
	v_pk_add_f32 v[36:37], v[110:111], v[36:37] op_sel_hi:[0,1]
	v_pk_fma_f32 v[36:37], v[62:63], v[62:63], v[36:37]
	v_mul_f32_e32 v114, v61, v61
	v_pk_add_f32 v[36:37], v[112:113], v[36:37] op_sel_hi:[0,1]
	v_pk_fma_f32 v[36:37], v[60:61], v[60:61], v[36:37]
	v_mul_f32_e32 v116, v97, v97
	v_pk_add_f32 v[36:37], v[114:115], v[36:37] op_sel_hi:[0,1]
	v_pk_fma_f32 v[36:37], v[96:97], v[96:97], v[36:37]
	v_pk_mul_f32 v[38:39], v[38:39], v[86:87] op_sel_hi:[1,0]
	v_pk_add_f32 v[36:37], v[116:117], v[36:37] op_sel_hi:[0,1]
	v_mul_f32_e32 v118, v39, v39
	v_pk_fma_f32 v[36:37], v[38:39], v[38:39], v[36:37]
	v_mul_f32_e32 v120, v93, v93
	v_pk_add_f32 v[36:37], v[118:119], v[36:37] op_sel_hi:[0,1]
	v_pk_fma_f32 v[36:37], v[92:93], v[92:93], v[36:37]
	v_mul_f32_e32 v122, v91, v91
	v_pk_add_f32 v[36:37], v[120:121], v[36:37] op_sel_hi:[0,1]
	v_pk_fma_f32 v[36:37], v[90:91], v[90:91], v[36:37]
	v_mul_f32_e32 v124, v43, v43
	v_pk_add_f32 v[36:37], v[122:123], v[36:37] op_sel_hi:[0,1]
	v_pk_fma_f32 v[36:37], v[42:43], v[42:43], v[36:37]
	v_mul_f32_e32 v126, v41, v41
	v_pk_add_f32 v[36:37], v[124:125], v[36:37] op_sel_hi:[0,1]
	v_pk_fma_f32 v[36:37], v[40:41], v[40:41], v[36:37]
	s_mov_b32 s2, 0x800000
	v_pk_add_f32 v[36:37], v[126:127], v[36:37] op_sel_hi:[0,1]
	v_mov_b32_e32 v98, v36
	s_nop 1
	v_permlane32_swap_b32_e32 v36, v98
	v_lshlrev_b32_e32 v128, 3, v87
	s_waitcnt vmcnt(25)
	v_pk_mul_f32 v[102:103], v[72:73], v[72:73]
	v_pk_mul_f32 v[100:101], v[74:75], v[74:75]
	s_waitcnt vmcnt(23)
	v_pk_fma_f32 v[102:103], v[76:77], v[76:77], v[102:103]
	v_pk_fma_f32 v[100:101], v[78:79], v[78:79], v[100:101]
	v_pk_add_f32 v[102:103], v[102:103], v[102:103] op_sel:[0,1] op_sel_hi:[1,0]
	v_pk_mul_f32 v[106:107], v[64:65], v[64:65]
	v_pk_add_f32 v[102:103], v[100:101], v[102:103]
	s_waitcnt vmcnt(22)
	v_pk_fma_f32 v[106:107], v[68:69], v[68:69], v[106:107]
	v_pk_add_f32 v[100:101], v[100:101], v[102:103] op_sel:[1,0] op_sel_hi:[0,1]
	v_pk_mul_f32 v[104:105], v[66:67], v[66:67]
	v_pk_add_f32 v[100:101], v[106:107], v[100:101]
	v_pk_fma_f32 v[104:105], v[70:71], v[70:71], v[104:105]
	v_pk_add_f32 v[100:101], v[106:107], v[100:101] op_sel:[1,0] op_sel_hi:[0,1]
	v_pk_add_f32 v[100:101], v[104:105], v[100:101]
	s_nop 0
	v_pk_add_f32 v[100:101], v[104:105], v[100:101] op_sel:[1,0] op_sel_hi:[0,1]
	v_mov_b32_e32 v99, v100
	s_nop 1
	v_permlane32_swap_b32_e32 v100, v99
	v_mov_b32_e32 v37, v100
	v_pk_add_f32 v[36:37], v[36:37], v[98:99]
	v_lshl_add_u64 v[98:99], v[84:85], 0, v[128:129]
	v_add_f32_e32 v36, v36, v37
	v_fmamk_f32 v36, v36, 0x3c2aaaab, v163
	v_mul_f32_e32 v37, 0x4b800000, v36
	v_cmp_gt_f32_e32 vcc, s2, v36
	s_nop 1
	v_cndmask_b32_e32 v36, v36, v37, vcc
	v_rsq_f32_e32 v36, v36
	s_nop 0
	v_mul_f32_e32 v37, 0x45800000, v36
	v_cndmask_b32_e32 v36, v36, v37, vcc
	v_pk_mul_f32 v[46:47], v[46:47], v[36:37] op_sel_hi:[1,0]
	v_pk_mul_f32 v[44:45], v[44:45], v[36:37] op_sel_hi:[1,0]
	s_waitcnt vmcnt(21)
	v_pk_mul_f32 v[32:33], v[198:199], v[46:47]
	v_pk_mul_f32 v[34:35], v[200:201], v[44:45]
	v_cvt_pk_bf16_f32 v32, v32, v33
	v_cvt_pk_bf16_f32 v33, v34, v35
	global_store_dwordx2 v[98:99], v[32:33], off
	v_pk_mul_f32 v[44:45], v[50:51], v[36:37] op_sel_hi:[1,0]
	v_pk_mul_f32 v[46:47], v[48:49], v[36:37] op_sel_hi:[1,0]
	v_pk_mul_f32 v[38:39], v[38:39], v[36:37] op_sel_hi:[1,0]
	v_pk_mul_f32 v[40:41], v[40:41], v[36:37] op_sel_hi:[1,0]
	v_cmp_gt_u32_e32 vcc, 32, v94
	s_waitcnt vmcnt(21)
	v_pk_mul_f32 v[32:33], v[202:203], v[44:45]
	v_pk_mul_f32 v[34:35], v[204:205], v[46:47]
	v_cvt_pk_bf16_f32 v32, v32, v33
	v_cvt_pk_bf16_f32 v33, v34, v35
	global_store_dwordx2 v[98:99], v[32:33], off offset:16
	v_pk_mul_f32 v[44:45], v[54:55], v[36:37] op_sel_hi:[1,0]
	v_pk_mul_f32 v[46:47], v[52:53], v[36:37] op_sel_hi:[1,0]
	s_waitcnt vmcnt(21)
	v_pk_mul_f32 v[32:33], v[206:207], v[44:45]
	v_pk_mul_f32 v[34:35], v[208:209], v[46:47]
	v_cvt_pk_bf16_f32 v32, v32, v33
	v_cvt_pk_bf16_f32 v33, v34, v35
	global_store_dwordx2 v[98:99], v[32:33], off offset:32
	v_pk_mul_f32 v[44:45], v[58:59], v[36:37] op_sel_hi:[1,0]
	v_pk_mul_f32 v[46:47], v[56:57], v[36:37] op_sel_hi:[1,0]
	s_waitcnt vmcnt(21)
	v_pk_mul_f32 v[32:33], v[210:211], v[44:45]
	v_pk_mul_f32 v[34:35], v[212:213], v[46:47]
	v_cvt_pk_bf16_f32 v32, v32, v33
	v_cvt_pk_bf16_f32 v33, v34, v35
	global_store_dwordx2 v[98:99], v[32:33], off offset:48
	v_pk_mul_f32 v[44:45], v[62:63], v[36:37] op_sel_hi:[1,0]
	v_pk_mul_f32 v[46:47], v[60:61], v[36:37] op_sel_hi:[1,0]
	s_waitcnt vmcnt(21)
	v_pk_mul_f32 v[32:33], v[214:215], v[44:45]
	v_pk_mul_f32 v[34:35], v[216:217], v[46:47]
	v_cvt_pk_bf16_f32 v32, v32, v33
	v_cvt_pk_bf16_f32 v33, v34, v35
	global_store_dwordx2 v[98:99], v[32:33], off offset:64
	v_pk_mul_f32 v[44:45], v[96:97], v[36:37] op_sel_hi:[1,0]
	s_waitcnt vmcnt(21)
	v_pk_mul_f32 v[34:35], v[38:39], v[220:221]
	v_pk_mul_f32 v[32:33], v[44:45], v[218:219]
	v_pk_mul_f32 v[38:39], v[92:93], v[36:37] op_sel_hi:[1,0]
	v_cvt_pk_bf16_f32 v32, v32, v33
	v_cvt_pk_bf16_f32 v33, v34, v35
	global_store_dwordx2 v[98:99], v[32:33], off offset:80
	v_pk_mul_f32 v[44:45], v[90:91], v[36:37] op_sel_hi:[1,0]
	s_waitcnt vmcnt(21)
	v_pk_mul_f32 v[32:33], v[38:39], v[222:223]
	v_pk_mul_f32 v[34:35], v[44:45], v[224:225]
	v_cvt_pk_bf16_f32 v32, v32, v33
	v_cvt_pk_bf16_f32 v33, v34, v35
	global_store_dwordx2 v[98:99], v[32:33], off offset:96
	v_pk_mul_f32 v[38:39], v[42:43], v[36:37] op_sel_hi:[1,0]
	s_waitcnt vmcnt(21)
	v_pk_mul_f32 v[34:35], v[40:41], v[228:229]
	v_pk_mul_f32 v[32:33], v[38:39], v[226:227]
	s_nop 0
	v_cvt_pk_bf16_f32 v32, v32, v33
	v_cvt_pk_bf16_f32 v33, v34, v35
	global_store_dwordx2 v[98:99], v[32:33], off offset:112
	v_lshrrev_b32_e32 v32, 6, v95
	v_and_b32_e32 v33, 63, v95
	v_cndmask_b32_e32 v32, v33, v32, vcc
	v_cvt_f32_u32_e32 v52, v32
	v_mov_b32_e32 v32, v73
	v_mov_b32_e32 v33, v77
	v_pk_mul_f32 v[32:33], v[32:33], v[36:37] op_sel_hi:[1,0]
	s_waitcnt vmcnt(21)
	v_mov_b32_e32 v34, v231
	s_waitcnt vmcnt(20)
	v_mov_b32_e32 v35, v233
	v_pk_mul_f32 v[32:33], v[32:33], v[34:35]
	s_and_saveexec_b64 s[2:3], s[0:1]
	s_cbranch_execz .LBB0_507
	v_mul_f32_e32 v34, v156, v52
	v_mul_f32_e32 v35, 0.15915494, v34
	v_sin_f32_e32 v38, v35
	v_cos_f32_e32 v34, v35
	v_pk_mul_f32 v[38:39], v[38:39], v[32:33] op_sel:[0,1] op_sel_hi:[0,0]
	v_pk_mul_f32 v[40:41], v[34:35], v[32:33] op_sel_hi:[0,1]
	v_pk_fma_f32 v[32:33], v[34:35], v[32:33], v[38:39] op_sel_hi:[0,1,1] neg_lo:[0,0,1] neg_hi:[0,0,1]
	v_add_f32_e32 v32, v40, v38
.LBB0_507:
	s_or_b64 exec, exec, s[2:3]
	v_mov_b32_e32 v37, v36
	v_mov_b32_e32 v38, v74
	v_mov_b32_e32 v39, v78
	v_pk_mul_f32 v[38:39], v[38:39], v[36:37]
	s_waitcnt vmcnt(18)
	v_pk_mul_f32 v[34:35], v[38:39], v[184:185]
	s_and_saveexec_b64 s[2:3], s[0:1]
	s_cbranch_execz .LBB0_509
	v_mul_f32_e32 v38, v157, v52
	v_mul_f32_e32 v39, 0.15915494, v38
	v_sin_f32_e32 v40, v39
	v_cos_f32_e32 v38, v39
	v_pk_mul_f32 v[40:41], v[40:41], v[34:35] op_sel:[0,1] op_sel_hi:[0,0]
	v_pk_mul_f32 v[42:43], v[38:39], v[34:35] op_sel_hi:[0,1]
	v_pk_fma_f32 v[34:35], v[38:39], v[34:35], v[40:41] op_sel_hi:[0,1,1] neg_lo:[0,0,1] neg_hi:[0,0,1]
	v_add_f32_e32 v34, v42, v40
.LBB0_509:
	s_or_b64 exec, exec, s[2:3]
	v_mov_b32_e32 v78, v75
	v_pk_mul_f32 v[40:41], v[78:79], v[36:37]
	s_waitcnt vmcnt(16)
	v_pk_mul_f32 v[38:39], v[40:41], v[186:187]
	s_and_saveexec_b64 s[2:3], s[0:1]
	s_cbranch_execz .LBB0_511
	v_mul_f32_e32 v40, v158, v52
	v_mul_f32_e32 v41, 0.15915494, v40
	v_sin_f32_e32 v42, v41
	v_cos_f32_e32 v40, v41
	v_pk_mul_f32 v[42:43], v[42:43], v[38:39] op_sel:[0,1] op_sel_hi:[0,0]
	v_pk_mul_f32 v[50:51], v[40:41], v[38:39] op_sel_hi:[0,1]
	v_pk_fma_f32 v[38:39], v[40:41], v[38:39], v[42:43] op_sel_hi:[0,1,1] neg_lo:[0,0,1] neg_hi:[0,0,1]
	v_add_f32_e32 v38, v50, v42
.LBB0_511:
	s_or_b64 exec, exec, s[2:3]
	v_mov_b32_e32 v42, v64
	v_mov_b32_e32 v43, v68
	v_pk_mul_f32 v[42:43], v[42:43], v[36:37]
	s_waitcnt vmcnt(14)
	v_pk_mul_f32 v[40:41], v[42:43], v[188:189]
	s_and_saveexec_b64 s[2:3], s[0:1]
	s_cbranch_execz .LBB0_513
	v_mul_f32_e32 v42, v159, v52
	v_mul_f32_e32 v43, 0.15915494, v42
	v_sin_f32_e32 v50, v43
	v_cos_f32_e32 v42, v43
	v_pk_mul_f32 v[50:51], v[50:51], v[40:41] op_sel:[0,1] op_sel_hi:[0,0]
	v_pk_mul_f32 v[54:55], v[42:43], v[40:41] op_sel_hi:[0,1]
	v_pk_fma_f32 v[40:41], v[42:43], v[40:41], v[50:51] op_sel_hi:[0,1,1] neg_lo:[0,0,1] neg_hi:[0,0,1]
	v_add_f32_e32 v40, v54, v50
.LBB0_513:
	s_or_b64 exec, exec, s[2:3]
	v_mov_b32_e32 v68, v65
	v_pk_mul_f32 v[50:51], v[68:69], v[36:37]
	s_waitcnt vmcnt(12)
	v_pk_mul_f32 v[42:43], v[50:51], v[190:191]
	s_and_saveexec_b64 s[2:3], s[0:1]
	s_cbranch_execz .LBB0_515
	v_mul_f32_e32 v45, v160, v52
	v_mul_f32_e32 v45, 0.15915494, v45
	v_sin_f32_e32 v54, v45
	v_cos_f32_e32 v50, v45
	v_pk_mul_f32 v[54:55], v[54:55], v[42:43] op_sel:[0,1] op_sel_hi:[0,0]
	v_pk_mul_f32 v[56:57], v[50:51], v[42:43] op_sel_hi:[0,1]
	v_pk_fma_f32 v[42:43], v[50:51], v[42:43], v[54:55] op_sel_hi:[0,1,1] neg_lo:[0,0,1] neg_hi:[0,0,1]
	v_add_f32_e32 v42, v56, v54
.LBB0_515:
	s_or_b64 exec, exec, s[2:3]
	v_mov_b32_e32 v54, v66
	v_mov_b32_e32 v55, v70
	v_pk_mul_f32 v[54:55], v[54:55], v[36:37]
	s_waitcnt vmcnt(10)
	v_pk_mul_f32 v[50:51], v[54:55], v[192:193]
	s_and_saveexec_b64 s[2:3], s[0:1]
	s_cbranch_execz .LBB0_517
	v_mul_f32_e32 v45, v161, v52
	v_mul_f32_e32 v45, 0.15915494, v45
	v_sin_f32_e32 v56, v45
	v_cos_f32_e32 v54, v45
	v_pk_mul_f32 v[56:57], v[56:57], v[50:51] op_sel:[0,1] op_sel_hi:[0,0]
	v_pk_mul_f32 v[58:59], v[54:55], v[50:51] op_sel_hi:[0,1]
	v_pk_fma_f32 v[50:51], v[54:55], v[50:51], v[56:57] op_sel_hi:[0,1,1] neg_lo:[0,0,1] neg_hi:[0,0,1]
	v_add_f32_e32 v50, v58, v56
.LBB0_517:
	s_or_b64 exec, exec, s[2:3]
	v_mov_b32_e32 v44, v230
	v_mov_b32_e32 v45, v232
	v_mov_b32_e32 v73, v76
	v_mov_b32_e32 v70, v67
	v_pk_mul_f32 v[54:55], v[72:73], v[36:37]
	v_pk_mul_f32 v[36:37], v[70:71], v[36:37]
	v_pk_mul_f32 v[44:45], v[54:55], v[44:45]
	s_waitcnt vmcnt(8)
	v_pk_mul_f32 v[36:37], v[36:37], v[234:235]
	s_and_saveexec_b64 s[2:3], s[0:1]
	s_cbranch_execz .LBB0_445
	v_mul_f32_e32 v47, 0.15915494, v52
	v_sin_f32_e32 v48, v47
	v_cos_f32_e32 v46, v47
	v_pk_mul_f32 v[48:49], v[48:49], v[44:45] op_sel:[0,1] op_sel_hi:[0,0]
	v_pk_mul_f32 v[54:55], v[46:47], v[44:45] op_sel_hi:[0,1]
	v_pk_fma_f32 v[44:45], v[46:47], v[44:45], v[48:49] op_sel_hi:[0,1,1] neg_lo:[0,0,1] neg_hi:[0,0,1]
	v_mul_f32_e32 v44, v162, v52
	v_mul_f32_e32 v46, 0.15915494, v44
	v_cos_f32_e32 v44, v46
	v_sin_f32_e32 v46, v46
	v_pk_mul_f32 v[52:53], v[44:45], v[36:37] op_sel_hi:[0,1]
	v_pk_mul_f32 v[46:47], v[46:47], v[36:37] op_sel:[0,1] op_sel_hi:[0,0]
	v_pk_fma_f32 v[36:37], v[44:45], v[36:37], v[46:47] op_sel_hi:[0,1,1] neg_lo:[0,0,1] neg_hi:[0,0,1]
	v_add_f32_e32 v44, v54, v48
	v_add_f32_e32 v36, v52, v46
	s_branch .LBB0_445
